# GDN prep 5b: zero-fill wait ladder removed (on top of masked fwd-subst update and row-pair scan finish)
# speedup vs baseline: 1.0011x; 1.0011x over previous
; __device__ __forceinline__ void gdn_preload(const Frame& F, int u, int t, GdnPre& P) {
;     ...
;     if (t < 384) {
;         const int pair = t % 96, rg = t / 96, c0 = 2 * pair, part = c0 >> 6, d0 = c0 & 63, zcol = part * 256 + h * 64 + d0;
;         const int rbase = row0 + rg * 16 - 2; const bf16_t* zc = F.Z + zcol;
; #pragma unroll
;         for (int rr = 0; rr < 20; ++rr) { int row = rbase + rr; row = row < seg_lo ? seg_lo : (row >= seg_hi ? seg_hi - 1 : row); P.raw[rr] = *(const unsigned*)(zc + (size_t)row * ZW); }
;         P.ga = 0; P.gb = 0;
;     } else {
;         const int tt = t - 384, d = tt >> 6, pp = tt & 63; const bf16_t* zr = F.Z + (size_t)(row0 + pp) * ZW;
;         P.ga = zr[ZC_GA + d * 4 + h]; P.gb = zr[ZC_GB + d * 4 + h];
; #pragma unroll
;         for (int rr = 0; rr < 20; ++rr) P.raw[rr] = 0u;
;     }
.LBB0_664:
	s_or_saveexec_b64 s[44:45], s[12:13]
	s_xor_b64 exec, exec, s[44:45]
	s_cbranch_execz .LBB0_666
	s_cmp_eq_u32 s9, 0
	s_cbranch_scc1 .LBB0_666
	global_load_dword v8, v[68:69], off
	global_load_dword v9, v[70:71], off
	global_load_dword v14, v[72:73], off
	global_load_dword v15, v[74:75], off
	global_load_dword v24, v[76:77], off
	global_load_dword v25, v[78:79], off
	global_load_dword v26, v[80:81], off
	global_load_dword v27, v[82:83], off
	global_load_dword v55, v[84:85], off
	global_load_dword v56, v[86:87], off
	global_load_dword v58, v[88:89], off
	global_load_dword v59, v[90:91], off
	global_load_dword v134, v[92:93], off
	global_load_dword v135, v[94:95], off
	global_load_dword v136, v[96:97], off
	global_load_dword v137, v[98:99], off
	global_load_dword v138, v[100:101], off
	global_load_dword v139, v[102:103], off
	global_load_dword v140, v[104:105], off
	global_load_dword v141, v[106:107], off
	v_mov_b32_e32 v2, 0
	v_mov_b32_e32 v3, 0
